# barrier waiters leave only when the XCD generation word equals gen+1 (robust against a stale read now that the last top-level arriver advances all XCD generation words)
# speedup vs baseline: 1.0109x; 1.0006x over previous
; __device__ __forceinline__ unsigned xb_ld(unsigned* p)              { return __hip_atomic_load(p, __ATOMIC_RELAXED, __HIP_MEMORY_SCOPE_AGENT); }
; __device__ __forceinline__ unsigned xb_add(unsigned* p, unsigned v) { return __hip_atomic_fetch_add(p, v, __ATOMIC_RELAXED, __HIP_MEMORY_SCOPE_AGENT); }
; #define XB_SPIN(cond, bar) do { unsigned _sp = 0; while (cond) { __builtin_amdgcn_s_sleep(1); \
;     if ((++_sp & 255u) == 0u) { if (xb_ld(&(bar)[XB_TMO])) break; if (_sp > XB_SPIN_CAP) { atomicAdd(&(bar)[XB_TMO], 1u); break; } } } } while (0)
; __device__ __forceinline__ void xcd_barrier(const XcdBarrier& b) {
;     ...
;         const unsigned old = xb_add(&bar[XB_XSUB(b.x)], 1u);
;         const unsigned gen = old / nloc;
;         if (old + 1u == (gen + 1u) * nloc) {
;             __builtin_amdgcn_fence(__ATOMIC_RELEASE, "agent");
;             asm volatile("s_waitcnt vmcnt(0)" ::: "memory");
;             const unsigned og = xb_add(&bar[XB_TOP], 1u);
;             const unsigned tg = og / nx;
;             if (og + 1u == (tg + 1u) * nx) xb_add(&bar[XB_TOPGEN], 1u);
;             else XB_SPIN(xb_ld(&bar[XB_TOPGEN]) == tg, bar);
;             __builtin_amdgcn_fence(__ATOMIC_ACQUIRE, "agent");
;             xb_add(&bar[XB_XGEN(b.x)], 1u);
;             asm volatile("s_waitcnt vmcnt(0)" ::: "memory");
;         } else {
;             XB_SPIN(xb_ld(&bar[XB_XGEN(b.x)]) == gen, bar);
.LBB0_433:
	s_or_b64 exec, exec, s[6:7]
	v_cvt_f32_u32_e32 v4, v2
	s_waitcnt vmcnt(0)
	v_readfirstlane_b32 s6, v3
	v_sub_u32_e32 v3, 0, v2
	v_rcp_iflag_f32_e32 v4, v4
	v_add_u32_e32 v5, s6, v1
	v_mul_f32_e32 v4, 0x4f7ffffe, v4
	v_cvt_u32_f32_e32 v4, v4
	v_mul_lo_u32 v1, v3, v4
	v_mul_hi_u32 v1, v4, v1
	v_add_u32_e32 v1, v4, v1
	v_mul_hi_u32 v1, v5, v1
	v_mul_lo_u32 v3, v1, v2
	v_sub_u32_e32 v3, v5, v3
	v_add_u32_e32 v4, 1, v1
	v_cmp_ge_u32_e32 vcc, v3, v2
	s_nop 1
	v_cndmask_b32_e32 v1, v1, v4, vcc
	v_sub_u32_e32 v4, v3, v2
	v_cndmask_b32_e32 v3, v3, v4, vcc
	v_add_u32_e32 v4, 1, v1
	v_cmp_ge_u32_e32 vcc, v3, v2
	v_add_u32_e32 v3, 1, v5
	s_nop 0
	v_cndmask_b32_e32 v1, v1, v4, vcc
	v_mul_lo_u32 v4, v2, v1
	v_add_u32_e32 v2, v4, v2
	v_cmp_ne_u32_e32 vcc, v3, v2
	s_and_saveexec_b64 s[6:7], vcc
	s_xor_b64 s[6:7], exec, s[6:7]
	s_cbranch_execz .LBB0_447
	s_waitcnt lgkmcnt(0)
	v_mov_b32_e32 v0, 0
	buffer_inv sc1
	v_add_u32_e32 v1, 1, v1
	global_load_dword v2, v0, s[94:95] sc1
	s_waitcnt vmcnt(0)
	v_cmp_ne_u32_e32 vcc, v2, v1
	s_and_saveexec_b64 s[8:9], vcc
	s_cbranch_execz .LBB0_446
	s_mov_b32 s16, 1
	s_mov_b64 s[10:11], 0
	s_branch .LBB0_437

; __device__ __forceinline__ unsigned xb_ld(unsigned* p)              { return __hip_atomic_load(p, __ATOMIC_RELAXED, __HIP_MEMORY_SCOPE_AGENT); }
; #define XB_SPIN(cond, bar) do { unsigned _sp = 0; while (cond) { __builtin_amdgcn_s_sleep(1); \
;     if ((++_sp & 255u) == 0u) { if (xb_ld(&(bar)[XB_TMO])) break; if (_sp > XB_SPIN_CAP) { atomicAdd(&(bar)[XB_TMO], 1u); break; } } } } while (0)
; __device__ __forceinline__ void xcd_barrier(const XcdBarrier& b) {
;     ...
;             XB_SPIN(xb_ld(&bar[XB_XGEN(b.x)]) == gen, bar);
.LBB0_439:
	global_load_dword v2, v0, s[94:95] sc1
	s_add_i32 s16, s16, 1
	s_mov_b64 s[50:51], -1
	s_waitcnt vmcnt(0)
	v_cmp_eq_u32_e32 vcc, v2, v1
	s_orn2_b64 s[46:47], vcc, exec
	s_branch .LBB0_436

; __device__ __forceinline__ unsigned xb_ld(unsigned* p)              { return __hip_atomic_load(p, __ATOMIC_RELAXED, __HIP_MEMORY_SCOPE_AGENT); }
; __device__ __forceinline__ unsigned xb_add(unsigned* p, unsigned v) { return __hip_atomic_fetch_add(p, v, __ATOMIC_RELAXED, __HIP_MEMORY_SCOPE_AGENT); }
; #define XB_SPIN(cond, bar) do { unsigned _sp = 0; while (cond) { __builtin_amdgcn_s_sleep(1); \
;     if ((++_sp & 255u) == 0u) { if (xb_ld(&(bar)[XB_TMO])) break; if (_sp > XB_SPIN_CAP) { atomicAdd(&(bar)[XB_TMO], 1u); break; } } } } while (0)
; __device__ __forceinline__ void xcd_barrier(const XcdBarrier& b) {
;     ...
;         const unsigned old = xb_add(&bar[XB_XSUB(b.x)], 1u);
;         const unsigned gen = old / nloc;
;         if (old + 1u == (gen + 1u) * nloc) {
;             __builtin_amdgcn_fence(__ATOMIC_RELEASE, "agent");
;             asm volatile("s_waitcnt vmcnt(0)" ::: "memory");
;             const unsigned og = xb_add(&bar[XB_TOP], 1u);
;             const unsigned tg = og / nx;
;             if (og + 1u == (tg + 1u) * nx) xb_add(&bar[XB_TOPGEN], 1u);
;             else XB_SPIN(xb_ld(&bar[XB_TOPGEN]) == tg, bar);
;             __builtin_amdgcn_fence(__ATOMIC_ACQUIRE, "agent");
;             xb_add(&bar[XB_XGEN(b.x)], 1u);
;             asm volatile("s_waitcnt vmcnt(0)" ::: "memory");
;         } else {
;             XB_SPIN(xb_ld(&bar[XB_XGEN(b.x)]) == gen, bar);
.LBB0_607:
	s_or_b64 exec, exec, s[8:9]
	v_cvt_f32_u32_e32 v4, v2
	s_waitcnt vmcnt(0)
	v_readfirstlane_b32 s8, v3
	v_sub_u32_e32 v3, 0, v2
	v_rcp_iflag_f32_e32 v4, v4
	v_add_u32_e32 v5, s8, v1
	v_mul_f32_e32 v4, 0x4f7ffffe, v4
	v_cvt_u32_f32_e32 v4, v4
	v_mul_lo_u32 v1, v3, v4
	v_mul_hi_u32 v1, v4, v1
	v_add_u32_e32 v1, v4, v1
	v_mul_hi_u32 v1, v5, v1
	v_mul_lo_u32 v3, v1, v2
	v_sub_u32_e32 v3, v5, v3
	v_add_u32_e32 v4, 1, v1
	v_cmp_ge_u32_e32 vcc, v3, v2
	s_nop 1
	v_cndmask_b32_e32 v1, v1, v4, vcc
	v_sub_u32_e32 v4, v3, v2
	v_cndmask_b32_e32 v3, v3, v4, vcc
	v_add_u32_e32 v4, 1, v1
	v_cmp_ge_u32_e32 vcc, v3, v2
	v_add_u32_e32 v3, 1, v5
	s_nop 0
	v_cndmask_b32_e32 v1, v1, v4, vcc
	v_mul_lo_u32 v4, v2, v1
	v_add_u32_e32 v2, v4, v2
	v_cmp_ne_u32_e32 vcc, v3, v2
	s_and_saveexec_b64 s[8:9], vcc
	s_xor_b64 s[8:9], exec, s[8:9]
	s_cbranch_execz .LBB0_621
	s_waitcnt lgkmcnt(0)
	v_mov_b32_e32 v0, 0
	buffer_inv sc1
	v_add_u32_e32 v1, 1, v1
	global_load_dword v2, v0, s[94:95] sc1
	s_waitcnt vmcnt(0)
	v_cmp_ne_u32_e32 vcc, v2, v1
	s_and_saveexec_b64 s[10:11], vcc
	s_cbranch_execz .LBB0_620
	s_mov_b32 s16, 1
	s_mov_b64 s[12:13], 0
	s_branch .LBB0_611

; __device__ __forceinline__ unsigned xb_ld(unsigned* p)              { return __hip_atomic_load(p, __ATOMIC_RELAXED, __HIP_MEMORY_SCOPE_AGENT); }
; #define XB_SPIN(cond, bar) do { unsigned _sp = 0; while (cond) { __builtin_amdgcn_s_sleep(1); \
;     if ((++_sp & 255u) == 0u) { if (xb_ld(&(bar)[XB_TMO])) break; if (_sp > XB_SPIN_CAP) { atomicAdd(&(bar)[XB_TMO], 1u); break; } } } } while (0)
; __device__ __forceinline__ void xcd_barrier(const XcdBarrier& b) {
;     ...
;             XB_SPIN(xb_ld(&bar[XB_XGEN(b.x)]) == gen, bar);
.LBB0_613:
	global_load_dword v2, v0, s[94:95] sc1
	s_add_i32 s16, s16, 1
	s_mov_b64 s[24:25], -1
	s_waitcnt vmcnt(0)
	v_cmp_eq_u32_e32 vcc, v2, v1
	s_orn2_b64 s[20:21], vcc, exec
	s_branch .LBB0_610

; __device__ __forceinline__ unsigned xb_ld(unsigned* p)              { return __hip_atomic_load(p, __ATOMIC_RELAXED, __HIP_MEMORY_SCOPE_AGENT); }
; __device__ __forceinline__ unsigned xb_add(unsigned* p, unsigned v) { return __hip_atomic_fetch_add(p, v, __ATOMIC_RELAXED, __HIP_MEMORY_SCOPE_AGENT); }
; #define XB_SPIN(cond, bar) do { unsigned _sp = 0; while (cond) { __builtin_amdgcn_s_sleep(1); \
;     if ((++_sp & 255u) == 0u) { if (xb_ld(&(bar)[XB_TMO])) break; if (_sp > XB_SPIN_CAP) { atomicAdd(&(bar)[XB_TMO], 1u); break; } } } } while (0)
; __device__ __forceinline__ void xcd_barrier(const XcdBarrier& b) {
;     ...
;         const unsigned old = xb_add(&bar[XB_XSUB(b.x)], 1u);
;         const unsigned gen = old / nloc;
;         if (old + 1u == (gen + 1u) * nloc) {
;             __builtin_amdgcn_fence(__ATOMIC_RELEASE, "agent");
;             asm volatile("s_waitcnt vmcnt(0)" ::: "memory");
;             const unsigned og = xb_add(&bar[XB_TOP], 1u);
;             const unsigned tg = og / nx;
;             if (og + 1u == (tg + 1u) * nx) xb_add(&bar[XB_TOPGEN], 1u);
;             else XB_SPIN(xb_ld(&bar[XB_TOPGEN]) == tg, bar);
;             __builtin_amdgcn_fence(__ATOMIC_ACQUIRE, "agent");
;             xb_add(&bar[XB_XGEN(b.x)], 1u);
;             asm volatile("s_waitcnt vmcnt(0)" ::: "memory");
;         } else {
;             XB_SPIN(xb_ld(&bar[XB_XGEN(b.x)]) == gen, bar);
.LBB0_735:
	s_or_b64 exec, exec, s[6:7]
	v_cvt_f32_u32_e32 v4, v2
	s_waitcnt vmcnt(0)
	v_readfirstlane_b32 s6, v3
	v_sub_u32_e32 v3, 0, v2
	v_rcp_iflag_f32_e32 v4, v4
	v_add_u32_e32 v5, s6, v1
	v_mul_f32_e32 v4, 0x4f7ffffe, v4
	v_cvt_u32_f32_e32 v4, v4
	v_mul_lo_u32 v1, v3, v4
	v_mul_hi_u32 v1, v4, v1
	v_add_u32_e32 v1, v4, v1
	v_mul_hi_u32 v1, v5, v1
	v_mul_lo_u32 v3, v1, v2
	v_sub_u32_e32 v3, v5, v3
	v_add_u32_e32 v4, 1, v1
	v_cmp_ge_u32_e32 vcc, v3, v2
	s_nop 1
	v_cndmask_b32_e32 v1, v1, v4, vcc
	v_sub_u32_e32 v4, v3, v2
	v_cndmask_b32_e32 v3, v3, v4, vcc
	v_add_u32_e32 v4, 1, v1
	v_cmp_ge_u32_e32 vcc, v3, v2
	v_add_u32_e32 v3, 1, v5
	s_nop 0
	v_cndmask_b32_e32 v1, v1, v4, vcc
	v_mul_lo_u32 v4, v2, v1
	v_add_u32_e32 v2, v4, v2
	v_cmp_ne_u32_e32 vcc, v3, v2
	s_and_saveexec_b64 s[6:7], vcc
	s_xor_b64 s[6:7], exec, s[6:7]
	s_cbranch_execz .LBB0_749
	s_waitcnt lgkmcnt(0)
	v_mov_b32_e32 v0, 0
	buffer_inv sc1
	v_add_u32_e32 v1, 1, v1
	global_load_dword v2, v0, s[94:95] sc1
	s_waitcnt vmcnt(0)
	v_cmp_ne_u32_e32 vcc, v2, v1
	s_and_saveexec_b64 s[8:9], vcc
	s_cbranch_execz .LBB0_748
	s_mov_b32 s20, 1
	s_mov_b64 s[10:11], 0
	s_branch .LBB0_739

; __device__ __forceinline__ unsigned xb_ld(unsigned* p)              { return __hip_atomic_load(p, __ATOMIC_RELAXED, __HIP_MEMORY_SCOPE_AGENT); }
; #define XB_SPIN(cond, bar) do { unsigned _sp = 0; while (cond) { __builtin_amdgcn_s_sleep(1); \
;     if ((++_sp & 255u) == 0u) { if (xb_ld(&(bar)[XB_TMO])) break; if (_sp > XB_SPIN_CAP) { atomicAdd(&(bar)[XB_TMO], 1u); break; } } } } while (0)
; __device__ __forceinline__ void xcd_barrier(const XcdBarrier& b) {
;     ...
;             XB_SPIN(xb_ld(&bar[XB_XGEN(b.x)]) == gen, bar);
.LBB0_741:
	global_load_dword v2, v0, s[94:95] sc1
	s_add_i32 s20, s20, 1
	s_mov_b64 s[16:17], -1
	s_waitcnt vmcnt(0)
	v_cmp_eq_u32_e32 vcc, v2, v1
	s_orn2_b64 s[14:15], vcc, exec
	s_branch .LBB0_738

; __device__ __forceinline__ unsigned xb_ld(unsigned* p)              { return __hip_atomic_load(p, __ATOMIC_RELAXED, __HIP_MEMORY_SCOPE_AGENT); }
; __device__ __forceinline__ unsigned xb_add(unsigned* p, unsigned v) { return __hip_atomic_fetch_add(p, v, __ATOMIC_RELAXED, __HIP_MEMORY_SCOPE_AGENT); }
; #define XB_SPIN(cond, bar) do { unsigned _sp = 0; while (cond) { __builtin_amdgcn_s_sleep(1); \
;     if ((++_sp & 255u) == 0u) { if (xb_ld(&(bar)[XB_TMO])) break; if (_sp > XB_SPIN_CAP) { atomicAdd(&(bar)[XB_TMO], 1u); break; } } } } while (0)
; __device__ __forceinline__ void xcd_barrier(const XcdBarrier& b) {
;     ...
;         const unsigned old = xb_add(&bar[XB_XSUB(b.x)], 1u);
;         const unsigned gen = old / nloc;
;         if (old + 1u == (gen + 1u) * nloc) {
;             __builtin_amdgcn_fence(__ATOMIC_RELEASE, "agent");
;             asm volatile("s_waitcnt vmcnt(0)" ::: "memory");
;             const unsigned og = xb_add(&bar[XB_TOP], 1u);
;             const unsigned tg = og / nx;
;             if (og + 1u == (tg + 1u) * nx) xb_add(&bar[XB_TOPGEN], 1u);
;             else XB_SPIN(xb_ld(&bar[XB_TOPGEN]) == tg, bar);
;             __builtin_amdgcn_fence(__ATOMIC_ACQUIRE, "agent");
;             xb_add(&bar[XB_XGEN(b.x)], 1u);
;             asm volatile("s_waitcnt vmcnt(0)" ::: "memory");
;         } else {
;             XB_SPIN(xb_ld(&bar[XB_XGEN(b.x)]) == gen, bar);
.LBB0_917:
	s_or_b64 exec, exec, s[8:9]
	v_cvt_f32_u32_e32 v4, v2
	s_waitcnt vmcnt(0)
	v_readfirstlane_b32 s8, v3
	v_sub_u32_e32 v3, 0, v2
	v_rcp_iflag_f32_e32 v4, v4
	v_add_u32_e32 v5, s8, v1
	v_mul_f32_e32 v4, 0x4f7ffffe, v4
	v_cvt_u32_f32_e32 v4, v4
	v_mul_lo_u32 v1, v3, v4
	v_mul_hi_u32 v1, v4, v1
	v_add_u32_e32 v1, v4, v1
	v_mul_hi_u32 v1, v5, v1
	v_mul_lo_u32 v3, v1, v2
	v_sub_u32_e32 v3, v5, v3
	v_add_u32_e32 v4, 1, v1
	v_cmp_ge_u32_e32 vcc, v3, v2
	s_nop 1
	v_cndmask_b32_e32 v1, v1, v4, vcc
	v_sub_u32_e32 v4, v3, v2
	v_cndmask_b32_e32 v3, v3, v4, vcc
	v_add_u32_e32 v4, 1, v1
	v_cmp_ge_u32_e32 vcc, v3, v2
	v_add_u32_e32 v3, 1, v5
	s_nop 0
	v_cndmask_b32_e32 v1, v1, v4, vcc
	v_mul_lo_u32 v4, v2, v1
	v_add_u32_e32 v2, v4, v2
	v_cmp_ne_u32_e32 vcc, v3, v2
	s_and_saveexec_b64 s[8:9], vcc
	s_xor_b64 s[8:9], exec, s[8:9]
	s_cbranch_execz .LBB0_931
	s_waitcnt lgkmcnt(0)
	v_mov_b32_e32 v0, 0
	buffer_inv sc1
	v_add_u32_e32 v1, 1, v1
	global_load_dword v2, v0, s[94:95] sc1
	s_waitcnt vmcnt(0)
	v_cmp_ne_u32_e32 vcc, v2, v1
	s_and_saveexec_b64 s[10:11], vcc
	s_cbranch_execz .LBB0_930
	s_mov_b32 s22, 1
	s_mov_b64 s[12:13], 0
	s_branch .LBB0_921

; __device__ __forceinline__ unsigned xb_ld(unsigned* p)              { return __hip_atomic_load(p, __ATOMIC_RELAXED, __HIP_MEMORY_SCOPE_AGENT); }
; #define XB_SPIN(cond, bar) do { unsigned _sp = 0; while (cond) { __builtin_amdgcn_s_sleep(1); \
;     if ((++_sp & 255u) == 0u) { if (xb_ld(&(bar)[XB_TMO])) break; if (_sp > XB_SPIN_CAP) { atomicAdd(&(bar)[XB_TMO], 1u); break; } } } } while (0)
; __device__ __forceinline__ void xcd_barrier(const XcdBarrier& b) {
;     ...
;             XB_SPIN(xb_ld(&bar[XB_XGEN(b.x)]) == gen, bar);
.LBB0_923:
	global_load_dword v2, v0, s[94:95] sc1
	s_add_i32 s22, s22, 1
	s_mov_b64 s[18:19], -1
	s_waitcnt vmcnt(0)
	v_cmp_eq_u32_e32 vcc, v2, v1
	s_orn2_b64 s[16:17], vcc, exec
	s_branch .LBB0_920

; __device__ __forceinline__ unsigned xb_ld(unsigned* p)              { return __hip_atomic_load(p, __ATOMIC_RELAXED, __HIP_MEMORY_SCOPE_AGENT); }
; __device__ __forceinline__ unsigned xb_add(unsigned* p, unsigned v) { return __hip_atomic_fetch_add(p, v, __ATOMIC_RELAXED, __HIP_MEMORY_SCOPE_AGENT); }
; #define XB_SPIN(cond, bar) do { unsigned _sp = 0; while (cond) { __builtin_amdgcn_s_sleep(1); \
;     if ((++_sp & 255u) == 0u) { if (xb_ld(&(bar)[XB_TMO])) break; if (_sp > XB_SPIN_CAP) { atomicAdd(&(bar)[XB_TMO], 1u); break; } } } } while (0)
; __device__ __forceinline__ void xcd_barrier(const XcdBarrier& b) {
;     ...
;         const unsigned old = xb_add(&bar[XB_XSUB(b.x)], 1u);
;         const unsigned gen = old / nloc;
;         if (old + 1u == (gen + 1u) * nloc) {
;             __builtin_amdgcn_fence(__ATOMIC_RELEASE, "agent");
;             asm volatile("s_waitcnt vmcnt(0)" ::: "memory");
;             const unsigned og = xb_add(&bar[XB_TOP], 1u);
;             const unsigned tg = og / nx;
;             if (og + 1u == (tg + 1u) * nx) xb_add(&bar[XB_TOPGEN], 1u);
;             else XB_SPIN(xb_ld(&bar[XB_TOPGEN]) == tg, bar);
;             __builtin_amdgcn_fence(__ATOMIC_ACQUIRE, "agent");
;             xb_add(&bar[XB_XGEN(b.x)], 1u);
;             asm volatile("s_waitcnt vmcnt(0)" ::: "memory");
;         } else {
;             XB_SPIN(xb_ld(&bar[XB_XGEN(b.x)]) == gen, bar);
.LBB0_1018:
	s_or_b64 exec, exec, s[4:5]
	v_cvt_f32_u32_e32 v4, v2
	s_waitcnt vmcnt(0)
	v_readfirstlane_b32 s4, v3
	v_sub_u32_e32 v3, 0, v2
	v_rcp_iflag_f32_e32 v4, v4
	v_add_u32_e32 v5, s4, v1
	v_mul_f32_e32 v4, 0x4f7ffffe, v4
	v_cvt_u32_f32_e32 v4, v4
	v_mul_lo_u32 v1, v3, v4
	v_mul_hi_u32 v1, v4, v1
	v_add_u32_e32 v1, v4, v1
	v_mul_hi_u32 v1, v5, v1
	v_mul_lo_u32 v3, v1, v2
	v_sub_u32_e32 v3, v5, v3
	v_add_u32_e32 v4, 1, v1
	v_cmp_ge_u32_e32 vcc, v3, v2
	s_nop 1
	v_cndmask_b32_e32 v1, v1, v4, vcc
	v_sub_u32_e32 v4, v3, v2
	v_cndmask_b32_e32 v3, v3, v4, vcc
	v_add_u32_e32 v4, 1, v1
	v_cmp_ge_u32_e32 vcc, v3, v2
	v_add_u32_e32 v3, 1, v5
	s_nop 0
	v_cndmask_b32_e32 v1, v1, v4, vcc
	v_mul_lo_u32 v4, v2, v1
	v_add_u32_e32 v2, v4, v2
	v_cmp_ne_u32_e32 vcc, v3, v2
	s_and_saveexec_b64 s[4:5], vcc
	s_xor_b64 s[4:5], exec, s[4:5]
	s_cbranch_execz .LBB0_1032
	s_waitcnt lgkmcnt(0)
	v_mov_b32_e32 v0, 0
	buffer_inv sc1
	v_add_u32_e32 v1, 1, v1
	global_load_dword v2, v0, s[94:95] sc1
	s_waitcnt vmcnt(0)
	v_cmp_ne_u32_e32 vcc, v2, v1
	s_and_saveexec_b64 s[6:7], vcc
	s_cbranch_execz .LBB0_1031
	s_mov_b32 s22, 1
	s_mov_b64 s[8:9], 0
	s_branch .LBB0_1022

; __device__ __forceinline__ unsigned xb_ld(unsigned* p)              { return __hip_atomic_load(p, __ATOMIC_RELAXED, __HIP_MEMORY_SCOPE_AGENT); }
; #define XB_SPIN(cond, bar) do { unsigned _sp = 0; while (cond) { __builtin_amdgcn_s_sleep(1); \
;     if ((++_sp & 255u) == 0u) { if (xb_ld(&(bar)[XB_TMO])) break; if (_sp > XB_SPIN_CAP) { atomicAdd(&(bar)[XB_TMO], 1u); break; } } } } while (0)
; __device__ __forceinline__ void xcd_barrier(const XcdBarrier& b) {
;     ...
;             XB_SPIN(xb_ld(&bar[XB_XGEN(b.x)]) == gen, bar);
.LBB0_1024:
	global_load_dword v2, v0, s[94:95] sc1
	s_add_i32 s22, s22, 1
	s_mov_b64 s[18:19], -1
	s_waitcnt vmcnt(0)
	v_cmp_eq_u32_e32 vcc, v2, v1
	s_orn2_b64 s[12:13], vcc, exec
	s_branch .LBB0_1021

; __device__ __forceinline__ unsigned xb_ld(unsigned* p)              { return __hip_atomic_load(p, __ATOMIC_RELAXED, __HIP_MEMORY_SCOPE_AGENT); }
; __device__ __forceinline__ unsigned xb_add(unsigned* p, unsigned v) { return __hip_atomic_fetch_add(p, v, __ATOMIC_RELAXED, __HIP_MEMORY_SCOPE_AGENT); }
; #define XB_SPIN(cond, bar) do { unsigned _sp = 0; while (cond) { __builtin_amdgcn_s_sleep(1); \
;     if ((++_sp & 255u) == 0u) { if (xb_ld(&(bar)[XB_TMO])) break; if (_sp > XB_SPIN_CAP) { atomicAdd(&(bar)[XB_TMO], 1u); break; } } } } while (0)
; __device__ __forceinline__ void xcd_barrier(const XcdBarrier& b) {
;     ...
;         const unsigned old = xb_add(&bar[XB_XSUB(b.x)], 1u);
;         const unsigned gen = old / nloc;
;         if (old + 1u == (gen + 1u) * nloc) {
;             __builtin_amdgcn_fence(__ATOMIC_RELEASE, "agent");
;             asm volatile("s_waitcnt vmcnt(0)" ::: "memory");
;             const unsigned og = xb_add(&bar[XB_TOP], 1u);
;             const unsigned tg = og / nx;
;             if (og + 1u == (tg + 1u) * nx) xb_add(&bar[XB_TOPGEN], 1u);
;             else XB_SPIN(xb_ld(&bar[XB_TOPGEN]) == tg, bar);
;             __builtin_amdgcn_fence(__ATOMIC_ACQUIRE, "agent");
;             xb_add(&bar[XB_XGEN(b.x)], 1u);
;             asm volatile("s_waitcnt vmcnt(0)" ::: "memory");
;         } else {
;             XB_SPIN(xb_ld(&bar[XB_XGEN(b.x)]) == gen, bar);
.LBB0_1218:
	s_or_b64 exec, exec, s[6:7]
	v_cvt_f32_u32_e32 v4, v2
	s_waitcnt vmcnt(0)
	v_readfirstlane_b32 s6, v3
	v_sub_u32_e32 v3, 0, v2
	v_rcp_iflag_f32_e32 v4, v4
	v_add_u32_e32 v5, s6, v1
	v_mul_f32_e32 v4, 0x4f7ffffe, v4
	v_cvt_u32_f32_e32 v4, v4
	v_mul_lo_u32 v1, v3, v4
	v_mul_hi_u32 v1, v4, v1
	v_add_u32_e32 v1, v4, v1
	v_mul_hi_u32 v1, v5, v1
	v_mul_lo_u32 v3, v1, v2
	v_sub_u32_e32 v3, v5, v3
	v_add_u32_e32 v4, 1, v1
	v_cmp_ge_u32_e32 vcc, v3, v2
	s_nop 1
	v_cndmask_b32_e32 v1, v1, v4, vcc
	v_sub_u32_e32 v4, v3, v2
	v_cndmask_b32_e32 v3, v3, v4, vcc
	v_add_u32_e32 v4, 1, v1
	v_cmp_ge_u32_e32 vcc, v3, v2
	v_add_u32_e32 v3, 1, v5
	s_nop 0
	v_cndmask_b32_e32 v1, v1, v4, vcc
	v_mul_lo_u32 v4, v2, v1
	v_add_u32_e32 v2, v4, v2
	v_cmp_ne_u32_e32 vcc, v3, v2
	s_and_saveexec_b64 s[6:7], vcc
	s_xor_b64 s[6:7], exec, s[6:7]
	s_cbranch_execz .LBB0_1232
	s_waitcnt lgkmcnt(0)
	v_mov_b32_e32 v0, 0
	buffer_inv sc1
	v_add_u32_e32 v1, 1, v1
	global_load_dword v2, v0, s[94:95] sc1
	s_waitcnt vmcnt(0)
	v_cmp_ne_u32_e32 vcc, v2, v1
	s_and_saveexec_b64 s[8:9], vcc
	s_cbranch_execz .LBB0_1231
	s_mov_b32 s22, 1
	s_mov_b64 s[10:11], 0
	s_branch .LBB0_1222

; __device__ __forceinline__ unsigned xb_ld(unsigned* p)              { return __hip_atomic_load(p, __ATOMIC_RELAXED, __HIP_MEMORY_SCOPE_AGENT); }
; __device__ __forceinline__ unsigned xb_add(unsigned* p, unsigned v) { return __hip_atomic_fetch_add(p, v, __ATOMIC_RELAXED, __HIP_MEMORY_SCOPE_AGENT); }
; #define XB_SPIN(cond, bar) do { unsigned _sp = 0; while (cond) { __builtin_amdgcn_s_sleep(1); \
;     if ((++_sp & 255u) == 0u) { if (xb_ld(&(bar)[XB_TMO])) break; if (_sp > XB_SPIN_CAP) { atomicAdd(&(bar)[XB_TMO], 1u); break; } } } } while (0)
; __device__ __forceinline__ void xcd_barrier(const XcdBarrier& b) {
;     ...
;         const unsigned old = xb_add(&bar[XB_XSUB(b.x)], 1u);
;         const unsigned gen = old / nloc;
;         if (old + 1u == (gen + 1u) * nloc) {
;             __builtin_amdgcn_fence(__ATOMIC_RELEASE, "agent");
;             asm volatile("s_waitcnt vmcnt(0)" ::: "memory");
;             const unsigned og = xb_add(&bar[XB_TOP], 1u);
;             const unsigned tg = og / nx;
;             if (og + 1u == (tg + 1u) * nx) xb_add(&bar[XB_TOPGEN], 1u);
;             else XB_SPIN(xb_ld(&bar[XB_TOPGEN]) == tg, bar);
;             __builtin_amdgcn_fence(__ATOMIC_ACQUIRE, "agent");
;             xb_add(&bar[XB_XGEN(b.x)], 1u);
;             asm volatile("s_waitcnt vmcnt(0)" ::: "memory");
;         } else {
;             XB_SPIN(xb_ld(&bar[XB_XGEN(b.x)]) == gen, bar);
.LBB0_1357:
	s_or_b64 exec, exec, s[2:3]
	v_cvt_f32_u32_e32 v4, v2
	s_waitcnt vmcnt(0)
	v_readfirstlane_b32 s2, v3
	v_sub_u32_e32 v3, 0, v2
	v_rcp_iflag_f32_e32 v4, v4
	v_add_u32_e32 v5, s2, v1
	v_mul_f32_e32 v4, 0x4f7ffffe, v4
	v_cvt_u32_f32_e32 v4, v4
	v_mul_lo_u32 v1, v3, v4
	v_mul_hi_u32 v1, v4, v1
	v_add_u32_e32 v1, v4, v1
	v_mul_hi_u32 v1, v5, v1
	v_mul_lo_u32 v3, v1, v2
	v_sub_u32_e32 v3, v5, v3
	v_add_u32_e32 v4, 1, v1
	v_cmp_ge_u32_e32 vcc, v3, v2
	s_nop 1
	v_cndmask_b32_e32 v1, v1, v4, vcc
	v_sub_u32_e32 v4, v3, v2
	v_cndmask_b32_e32 v3, v3, v4, vcc
	v_add_u32_e32 v4, 1, v1
	v_cmp_ge_u32_e32 vcc, v3, v2
	v_add_u32_e32 v3, 1, v5
	s_nop 0
	v_cndmask_b32_e32 v1, v1, v4, vcc
	v_mul_lo_u32 v4, v2, v1
	v_add_u32_e32 v2, v4, v2
	v_cmp_ne_u32_e32 vcc, v3, v2
	s_and_saveexec_b64 s[2:3], vcc
	s_xor_b64 s[2:3], exec, s[2:3]
	s_cbranch_execz .LBB0_1371
	s_waitcnt lgkmcnt(0)
	v_mov_b32_e32 v0, 0
	buffer_inv sc1
	v_add_u32_e32 v1, 1, v1
	global_load_dword v2, v0, s[94:95] sc1
	s_waitcnt vmcnt(0)
	v_cmp_ne_u32_e32 vcc, v2, v1
	s_and_saveexec_b64 s[4:5], vcc
	s_cbranch_execz .LBB0_1370
	s_mov_b32 s16, 1
	s_mov_b64 s[6:7], 0
	s_branch .LBB0_1361

; __device__ __forceinline__ unsigned xb_ld(unsigned* p)              { return __hip_atomic_load(p, __ATOMIC_RELAXED, __HIP_MEMORY_SCOPE_AGENT); }
; #define XB_SPIN(cond, bar) do { unsigned _sp = 0; while (cond) { __builtin_amdgcn_s_sleep(1); \
;     if ((++_sp & 255u) == 0u) { if (xb_ld(&(bar)[XB_TMO])) break; if (_sp > XB_SPIN_CAP) { atomicAdd(&(bar)[XB_TMO], 1u); break; } } } } while (0)
; __device__ __forceinline__ void xcd_barrier(const XcdBarrier& b) {
;     ...
;             XB_SPIN(xb_ld(&bar[XB_XGEN(b.x)]) == gen, bar);
.LBB0_1363:
	global_load_dword v2, v0, s[94:95] sc1
	s_add_i32 s16, s16, 1
	s_mov_b64 s[12:13], -1
	s_waitcnt vmcnt(0)
	v_cmp_eq_u32_e32 vcc, v2, v1
	s_orn2_b64 s[10:11], vcc, exec
	s_branch .LBB0_1360
